# placement: attention tile loop shifted by 4 bytes (one s_nop before the loop head, one after the loop)
# speedup vs baseline: 1.0157x; 1.0031x over previous
; DI void attn_item(const Params& p, int item, char* smem) {
;     ...
;   const int tid = tid__, lane = tid & 63, wave = tid >> 6, r32 = lane & 31, hi = lane >> 5;
;   int bh, qpos0, key0, nkt, orow0;
;   if (item < 2048) { bh = item >> 5; const int qb = item & 31; qpos0 = qb * 128; key0 = 0; nkt = LK / 64; orow0 = (bh >> 3) * L + qpos0; }
;   else { const int it = item - 2048; bh = it >> 1; const int qb = it & 1; qpos0 = 4096 + qb * 128; key0 = 4096; nkt = LC / 64; orow0 = NTL + (bh >> 3) * LC + qb * 128; }
;   const int h = bh & 7;
;   const u16* Qp = (const u16*)(p.ws + OFF_R1) + ((size_t)bh * LK + qpos0 + wave * 32 + r32) * 96 + hi * 8;
;   const u16* Kp = (const u16*)(p.ws + OFF_R1 + SZ_Q) + ((size_t)bh * LK + key0) * 96;
;   const u16* Vp = (const u16*)(p.ws + OFF_R1 + 2 * SZ_Q) + (size_t)bh * 64 * LK + key0;
;   u16* Ks = (u16*)smem;
;   u16* Vs = Ks + 2 * 64 * KSL;
;   bf16x8 qr[6];
; #pragma unroll
;   for (int d0 = 0; d0 < 6; ++d0) qr[d0] = *(const bf16x8*)(Qp + d0 * 16);
;   uint4 ak0, ak1, ak2, av0, av1, bk0, bk1, bk2, bv0, bv1;
;   const int kr0 = tid / 12, kc0 = tid - kr0 * 12, kr1 = (tid + 256) / 12, kc1 = (tid + 256) - kr1 * 12, kr2 = (tid + 512) / 12, kc2 = (tid + 512) - kr2 * 12;
;   const int vd0 = tid >> 3, vc0 = tid & 7, vd1 = vd0 + 32;
;     ...
;   f32x16 o0, o1;
; #pragma unroll
;   for (int i = 0; i < 16; ++i) { o0[i] = 0.f; o1[i] = 0.f; }
;     ...
;   __syncthreads();
;   gload(a, 0); lstore(a, 0);
;   gload(a, 1);
;   __syncthreads();
.LBB0_528:
	v_ashrrev_i32_e32 v0, 1, v2
	v_and_b32_e32 v3, 31, v2
	v_and_b32_e32 v0, 0xffffffe0, v0
	v_ashrrev_i32_e32 v137, 31, v0
	v_or_b32_e32 v136, v0, v3
	s_waitcnt vmcnt(0)
	v_lshl_add_u64 v[4:5], v[136:137], 0, s[64:65]
	v_mov_b32_e32 v0, 0x1100
	v_mad_i64_i32 v[4:5], s[6:7], s8, v0, v[4:5]
	v_mov_b64_e32 v[6:7], s[60:61]
	v_bfe_u32 v44, v2, 5, 1
	v_mad_u64_u32 v[6:7], s[6:7], v4, s72, v[6:7]
	v_mad_i32_i24 v7, v5, s72, v7
	v_lshlrev_b32_e32 v0, 4, v44
	v_lshl_add_u64 v[4:5], v[6:7], 0, v[0:1]
	flat_load_dwordx4 v[80:83], v[4:5]
	flat_load_dwordx4 v[84:87], v[4:5] offset:32
	flat_load_dwordx4 v[88:91], v[4:5] offset:64
	flat_load_dwordx4 v[92:95], v[4:5] offset:96
	flat_load_dwordx4 v[96:99], v[4:5] offset:128
	flat_load_dwordx4 v[100:103], v[4:5] offset:160
	v_mul_hi_i32 v4, v2, s73
	s_mul_i32 s12, s8, 0x1100
	v_lshrrev_b32_e32 v5, 31, v4
	v_ashrrev_i32_e32 v4, 1, v4
	s_mul_hi_i32 s11, s8, 0x1100
	s_add_u32 s6, s12, s4
	v_add_u32_e32 v45, v4, v5
	v_add_u32_e32 v4, 0x100, v2
	s_addc_u32 s5, s11, s5
	v_mul_hi_i32 v5, v4, s73
	s_mulk_i32 s5, 0xc0
	s_mul_hi_u32 s7, s6, 0xc0
	v_lshrrev_b32_e32 v6, 31, v5
	v_ashrrev_i32_e32 v5, 1, v5
	s_add_i32 s7, s7, s5
	s_mul_i32 s11, s8, 0x88000
	v_readlane_b32 s12, v254, 15
	v_add_u32_e32 v46, v5, v6
	v_add_u32_e32 v6, 0x200, v2
	s_mul_hi_i32 s5, s8, 0x88000
	v_readlane_b32 s13, v254, 16
	s_add_u32 s11, s12, s11
	v_mul_hi_i32 v5, v6, s73
	s_mulk_i32 s6, 0xc0
	s_addc_u32 s5, s13, s5
	v_readlane_b32 s12, v254, 17
	v_lshrrev_b32_e32 v7, 31, v5
	v_ashrrev_i32_e32 v5, 1, v5
	v_readlane_b32 s13, v254, 18
	s_add_u32 s6, s12, s6
	v_add_u32_e32 v47, v5, v7
	s_addc_u32 s7, s13, s7
	s_lshl_b32 s64, s4, 1
	v_mad_u64_u32 v[24:25], s[14:15], v45, -12, v[2:3]
	v_mad_u64_u32 v[26:27], s[14:15], v46, -12, v[4:5]
	v_mad_u64_u32 v[28:29], s[14:15], v47, -12, v[6:7]
	s_add_u32 s12, s11, s64
	v_lshlrev_b32_e32 v6, 3, v24
	v_lshlrev_b32_e32 v8, 3, v26
	v_lshlrev_b32_e32 v14, 3, v28
	v_ashrrev_i32_e32 v48, 3, v2
	s_addc_u32 s13, s5, 0
	v_mov_b64_e32 v[30:31], s[6:7]
	v_ashrrev_i32_e32 v7, 31, v6
	v_ashrrev_i32_e32 v9, 31, v8
	v_ashrrev_i32_e32 v15, 31, v14
	v_add_u32_e32 v18, 32, v48
	v_mad_i64_i32 v[4:5], s[6:7], v45, s72, v[30:31]
	v_lshlrev_b64 v[32:33], 1, v[6:7]
	v_mad_i64_i32 v[6:7], s[6:7], v46, s72, v[30:31]
	v_lshlrev_b64 v[34:35], 1, v[8:9]
	v_mad_i64_i32 v[12:13], s[6:7], v47, s72, v[30:31]
	v_lshlrev_b64 v[36:37], 1, v[14:15]
	v_mov_b64_e32 v[14:15], s[12:13]
	s_movk_i32 s11, 0x2200
	v_lshlrev_b32_e32 v19, 4, v2
	v_lshl_add_u64 v[4:5], v[4:5], 0, v[32:33]
	v_lshl_add_u64 v[8:9], v[6:7], 0, v[34:35]
	v_lshl_add_u64 v[12:13], v[12:13], 0, v[36:37]
	v_mad_i64_i32 v[16:17], s[6:7], v48, s11, v[14:15]
	v_and_b32_e32 v38, 0x70, v19
	v_mov_b32_e32 v39, v1
	v_mad_i64_i32 v[14:15], s[6:7], v18, s11, v[14:15]
	s_waitcnt lgkmcnt(0)
	s_barrier
	flat_load_dwordx4 v[4:7], v[4:5]
	s_nop 0
	flat_load_dwordx4 v[8:11], v[8:9]
	v_lshl_add_u64 v[40:41], v[16:17], 0, v[38:39]
	v_lshl_add_u64 v[42:43], v[14:15], 0, v[38:39]
	flat_load_dwordx4 v[12:15], v[12:13]
	s_nop 0
	flat_load_dwordx4 v[16:19], v[40:41]
	flat_load_dwordx4 v[20:23], v[42:43]
	s_movk_i32 s5, 0xd0
	v_mul_lo_u32 v25, v45, s5
	v_lshl_add_u32 v150, v24, 4, v25
	v_mul_lo_u32 v24, v46, s5
	v_lshl_add_u32 v151, v26, 4, v24
	v_mul_lo_u32 v24, v47, s5
	s_movk_i32 s5, 0x88
	v_mad_u64_u32 v[138:139], s[6:7], v48, s5, v[38:39]
	v_lshl_add_u32 v152, v28, 4, v24
	v_add_u32_e32 v139, 0x6800, v138
	v_add_u32_e32 v24, 0x7900, v138
	s_waitcnt vmcnt(0) lgkmcnt(0)
	ds_write_b128 v150, v[4:7]
	ds_write_b128 v151, v[8:11]
	ds_write_b128 v152, v[12:15]
	ds_write2_b64 v139, v[16:17], v[18:19] offset1:1
	ds_write2_b64 v24, v[20:21], v[22:23] offset1:1
	v_add_u32_e32 v4, 64, v45
	v_mad_i64_i32 v[4:5], s[6:7], v4, s72, v[30:31]
	v_add_u32_e32 v6, 64, v46
	v_lshl_add_u64 v[4:5], v[4:5], 0, v[32:33]
	v_mad_i64_i32 v[6:7], s[6:7], v6, s72, v[30:31]
	v_lshl_add_u64 v[6:7], v[6:7], 0, v[34:35]
	flat_load_dwordx4 v[104:107], v[4:5]
	flat_load_dwordx4 v[108:111], v[6:7]
	v_add_u32_e32 v4, 64, v47
	v_mad_i64_i32 v[4:5], s[6:7], v4, s72, v[30:31]
	v_lshl_add_u64 v[4:5], v[4:5], 0, v[36:37]
	flat_load_dwordx4 v[112:115], v[4:5]
	flat_load_dwordx4 v[116:119], v[40:41] offset:128
	flat_load_dwordx4 v[120:123], v[42:43] offset:128
	v_mul_u32_u24_e32 v7, 0x68, v3
	v_lshlrev_b32_e32 v7, 1, v7
	v_lshlrev_b32_e32 v6, 3, v44
	v_add_u32_e32 v154, v7, v0
	v_mul_i32_i24_e32 v0, 0xffffffb8, v3
	v_mad_i64_i32 v[4:5], s[6:7], v48, s11, 0
	v_add3_u32 v155, v7, v0, v6
	v_mov_b32_e32 v0, 0x88000
	v_mad_i64_i32 v[4:5], s[6:7], s8, v0, v[4:5]
	s_mul_i32 s6, s8, 0xcc000
	s_mulk_i32 s4, 0xc0
	s_mul_hi_i32 s5, s8, 0xcc000
	s_add_u32 s4, s6, s4
	v_and_b32_e32 v0, 7, v2
	s_addc_u32 s5, s5, 0
	v_lshl_or_b32 v4, v0, 4, v4
	v_mov_b64_e32 v[2:3], s[4:5]
	v_lshl_add_u64 v[140:141], v[4:5], 0, s[64:65]
	v_mad_i64_i32 v[4:5], s[4:5], v47, s72, v[2:3]
	v_lshl_add_u64 v[142:143], v[4:5], 0, v[36:37]
	v_mad_i64_i32 v[4:5], s[4:5], v46, s72, v[2:3]
	v_mad_i64_i32 v[2:3], s[4:5], v45, s72, v[2:3]
	v_mov_b32_e32 v14, v1
	v_mov_b32_e32 v15, v1
	v_lshlrev_b32_e32 v137, 2, v44
	v_lshl_add_u64 v[144:145], v[4:5], 0, v[34:35]
	v_lshl_add_u64 v[146:147], v[2:3], 0, v[32:33]
	v_mov_b32_e32 v0, v1
	v_mov_b32_e32 v2, v1
	v_mov_b32_e32 v3, v1
	v_mov_b32_e32 v4, v1
	v_mov_b32_e32 v5, v1
	v_mov_b32_e32 v6, v1
	v_mov_b32_e32 v7, v1
	v_mov_b32_e32 v8, v1
	v_mov_b32_e32 v9, v1
	v_mov_b32_e32 v10, v1
	v_mov_b32_e32 v11, v1
	v_mov_b32_e32 v12, v1
	v_mov_b32_e32 v13, v1
	v_mov_b64_e32 v[30:31], v[14:15]
	v_mov_b64_e32 v[46:47], v[14:15]
	v_add_u32_e32 v153, 0x1100, v138
	v_add_u32_e32 v224, 0x7800, v155
	v_add_u32_e32 v225, 0x6800, v155
	v_add_u32_e32 v226, 0x8a00, v138
	v_add_u32_e32 v227, 0x8a00, v153
	v_add_u32_e32 v228, 0x8800, v155
	v_add_u32_e32 v229, 0x9800, v155
	v_add_u32_e32 v230, 0x6800, v153
	s_mov_b32 s12, 0
	v_mov_b32_e32 v156, 0xf149f2ca
	v_mov_b32_e32 v196, 0
	v_mov_b32_e32 v197, 0
	v_mov_b32_e32 v198, 0
	v_mov_b32_e32 v199, 0
	v_mov_b32_e32 v200, 0
	v_mov_b32_e32 v201, 0
	v_mov_b32_e32 v202, 0
	v_mov_b32_e32 v203, 0
	v_mov_b32_e32 v204, 0
	v_mov_b32_e32 v205, 0
	v_mov_b32_e32 v206, 0
	v_mov_b32_e32 v207, 0
	v_mov_b32_e32 v208, 0
	v_mov_b32_e32 v209, 0
	v_mov_b32_e32 v210, 0
	v_mov_b32_e32 v211, 0
	s_mov_b32 s98, 0xff800000
	s_mov_b32 s99, 0xff800000
	v_mov_b32_e32 v157, 0
	v_mov_b64_e32 v[28:29], v[12:13]
	v_mov_b64_e32 v[26:27], v[10:11]
	v_mov_b64_e32 v[24:25], v[8:9]
	v_mov_b64_e32 v[22:23], v[6:7]
	v_mov_b64_e32 v[20:21], v[4:5]
	v_mov_b64_e32 v[18:19], v[2:3]
	v_mov_b64_e32 v[16:17], v[0:1]
	v_mov_b64_e32 v[44:45], v[12:13]
	v_mov_b64_e32 v[42:43], v[10:11]
	v_mov_b64_e32 v[40:41], v[8:9]
	v_mov_b64_e32 v[38:39], v[6:7]
	v_mov_b64_e32 v[36:37], v[4:5]
	v_mov_b64_e32 v[34:35], v[2:3]
	v_mov_b64_e32 v[32:33], v[0:1]
	s_waitcnt lgkmcnt(0)
	s_barrier
	s_nop 0

; DI void phase_attn(const Params& p, int l, char* smem) {
;     ...
;   for (;;) {
;     __syncthreads();
;     if (tid__ == 0) qslot_sh = (int)__hip_atomic_fetch_add(ctr, 1u, __ATOMIC_RELAXED, __HIP_MEMORY_SCOPE_AGENT);
;     __syncthreads();
;     const int it = qslot_sh;
;     if (it >= nattn) break;
;     attn_item(p, it, smem);
.LBB0_541:
	s_nop 0
	s_mov_b64 s[0:1], 0
